# v015 with the attention static priority raise moved to waves 0-3 (A/B of which half to raise)
# speedup vs baseline: 1.0070x; 1.0070x over previous
; #define LAS __attribute__((address_space(3)))
; __device__ __forceinline__ float cnt_same(int d) { const int ad = d < 0 ? -d : d; return (float)((ad <= 16 ? 1 : 0) + (ad <= 64 ? 1 : 0) + ((((d & 3) == 0) && ad <= 256) ? 1 : 0)); }
; __global__ void __launch_bounds__(512, 2) fwd_megakernel(Args a) {
;     ...
;         LAS unsigned char* vl = lds + wave * 8192;
;         LAS f32x4* ctf = (LAS f32x4*)(lds + 65536);
;         LAS float* cfar = (LAS float*)(lds + 65536 + 55 * 64 * 16);
;         __syncthreads();
;         for (int i = tid; i < 55 * 64; i += 512) {
;             const int ix = i >> 6, ln = i & 63, lfr = ln & 15, lfq = ln >> 4; f32x4 cn;
; #pragma unroll
;             for (int r = 0; r < 4; ++r) {
;                 if (ix < 33) cn[r] = cnt_same((ix * 16 - 256) + 4 * lfq + r - lfr);
;                 else if (ix >= 54) cn[r] = 0.f;
;                 else { const int e = ix - 33, drr = e / 3 - 3, T = (e % 3) * 16 - 16; cn[r] = drr == 0 ? 0.f : cnt_other(T + 4 * lfq + r - lfr, drr); }
;             }
;             ctf[i] = cn;
;             if (ix < 34) cfar[i] = ix < 33 ? cnt_same((ix * 16 - 256) + 4 * lfq + (lfr & 3) - lfr) : 0.f;
;         }
;         __syncthreads();
;         const int vcu = (G % 8 == 0) ? (c % 8) * (G / 8) + c / 8 : c;
;         const int gw = vcu * 8 + wave, NGW = G * 8;
;     ...
;         for (int task = gw; task < NBATCH * NHEAD * 128; task += NGW) attn_task<DRY_ATTN>(vl, ctf, cfar, MG, (bf16_t*)(ws + 196 * MiB), AW, KB, VB, (float*)(ws + 3 * MiB), task, lane);
;     ...
;         for (int task = gw; task < NBATCH * NHEAD * 128; task += NGW) attn_task<0>(vl, ctf, cfar, MG, MG, DM, KB, VB, ssqa, task, lane);
.LBB0_543:
	s_lshl_b32 s0, s1, 13
	s_add_i32 s59, s0, 0
	s_cmp_ge_u32 s1, 4
	s_cbranch_scc1 .Lmy_attn_prio_done
	s_setprio 1
